# split grid barrier after the conv phase: wait + acquire deferred past the mLSTM item prologue (zero-fill, gate scans, recurrence)
# speedup vs baseline: 1.0186x; 1.0055x over previous
; __device__ __forceinline__ unsigned xb_ld(unsigned* p)              { return __hip_atomic_load(p, __ATOMIC_RELAXED, __HIP_MEMORY_SCOPE_AGENT); }
; __device__ __forceinline__ void xcd_barrier_complete(unsigned* bar, unsigned x, unsigned& nloc, unsigned& nx) {
;     const unsigned G = gridDim.x * gridDim.y * gridDim.z;
;     unsigned sum, cnt, mine, sp = 0u;
;     for (;;) {
;         sum = 0u; cnt = 0u; mine = 0u;
; #pragma unroll
;         for (unsigned j = 0; j < 16; ++j) { const unsigned c = xb_ld(&bar[XB_XCNT(j)]); sum += c; cnt += (c > 0u) ? 1u : 0u; mine = (j == x) ? c : mine; }
; __device__ __forceinline__ void xcd_barrier(const XcdBarrier& b) {
;     asm volatile("s_waitcnt vmcnt(0)" ::: "memory");
;     __syncthreads();
;     if (threadIdx.x == 0) {
;         unsigned* bar = b.bar;
;         __builtin_amdgcn_s_waitcnt(0);
;         unsigned nloc = b.st[0], nx = b.st[1];
;         if (nloc == 0u) { xcd_barrier_complete(bar, b.x, nloc, nx); b.st[0] = nloc; b.st[1] = nx; }
.LBB0_183:
	s_mov_b32 s98, 0
	s_cmp_gt_i32 s91, 3
	s_cselect_b64 s[2:3], -1, 0
	s_and_b64 s[0:1], s[0:1], s[2:3]
	s_andn2_b64 vcc, exec, s[0:1]
	s_cbranch_vccnz .LBB0_233
	s_cmp_eq_u32 s82, 0x100
	s_cselect_b32 s98, 1, 0
	s_waitcnt vmcnt(0)
	s_waitcnt vmcnt(0) lgkmcnt(0)
	s_barrier
	s_mov_b64 s[0:1], exec
	v_readlane_b32 s4, v254, 1
	v_readlane_b32 s5, v254, 2
	s_and_b64 s[4:5], s[0:1], s[4:5]
	s_mov_b64 exec, s[4:5]
	s_cbranch_execz .LBB0_232
	v_readlane_b32 s4, v254, 22
	s_waitcnt vmcnt(0) expcnt(0) lgkmcnt(0)
	s_nop 0
	v_mov_b32_e32 v0, s4
	ds_read_b32 v2, v0
	ds_read_b32 v0, v0 offset:4
	s_waitcnt lgkmcnt(1)
	v_cmp_ne_u32_e32 vcc, 0, v2
	s_cbranch_vccnz .LBB0_200
	v_readlane_b32 s4, v254, 0
	s_mul_i32 s33, s83, s4
	s_add_u32 s4, s88, 0xffc0200
	s_addc_u32 s5, s89, 0
	s_add_u32 s6, s88, 0xffc0400
	s_addc_u32 s7, s89, 0
	s_add_u32 s8, s88, 0xffc0500
	s_addc_u32 s9, s89, 0
	s_add_u32 s10, s88, 0xffc0600
	s_addc_u32 s11, s89, 0
	s_add_u32 s12, s88, 0xffc0700
	s_addc_u32 s13, s89, 0
	s_add_u32 s14, s88, 0xffc0800
	s_addc_u32 s15, s89, 0
	s_add_u32 s16, s88, 0xffc0900
	s_addc_u32 s17, s89, 0
	s_add_u32 s18, s88, 0xffc0a00
	s_addc_u32 s19, s89, 0
	s_add_u32 s20, s88, 0xffc0b00
	s_addc_u32 s21, s89, 0
	s_add_u32 s22, s88, 0xffc0c00
	s_addc_u32 s23, s89, 0
	s_add_u32 s24, s88, 0xffc0d00
	s_addc_u32 s25, s89, 0
	s_add_u32 s26, s88, 0xffc0e00
	s_addc_u32 s27, s89, 0
	s_add_u32 s28, s88, 0xffc0f00
	s_addc_u32 s29, s89, 0
	s_add_u32 s30, s88, 0xffc1000
	s_addc_u32 s31, s89, 0
	s_add_u32 s34, s88, 0xffc1100
	s_addc_u32 s35, s89, 0
	s_add_u32 s36, s88, 0xffc1200
	s_addc_u32 s37, s89, 0
	s_add_u32 s38, s88, 0xffc1300
	s_mul_i32 s33, s33, s82
	s_addc_u32 s39, s89, 0
	s_mov_b32 s46, 1
	v_mov_b32_e32 v16, 0
	s_branch .LBB0_188

; __device__ __forceinline__ unsigned xb_ld(unsigned* p)              { return __hip_atomic_load(p, __ATOMIC_RELAXED, __HIP_MEMORY_SCOPE_AGENT); }
; __device__ __forceinline__ unsigned xb_add(unsigned* p, unsigned v) { return __hip_atomic_fetch_add(p, v, __ATOMIC_RELAXED, __HIP_MEMORY_SCOPE_AGENT); }
; #define XB_SPIN(cond, bar) do { unsigned _sp = 0; while (cond) { __builtin_amdgcn_s_sleep(1); \
;     if ((++_sp & 255u) == 0u) { if (xb_ld(&(bar)[XB_TMO])) break; if (_sp > XB_SPIN_CAP) { atomicAdd(&(bar)[XB_TMO], 1u); break; } } } } while (0)
; __device__ __forceinline__ void xcd_barrier(const XcdBarrier& b) {
;     ...
;         const unsigned old = xb_add(&bar[XB_XSUB(b.x)], 1u);
;         const unsigned gen = old / nloc;
;         if (old + 1u == (gen + 1u) * nloc) {
;             __builtin_amdgcn_fence(__ATOMIC_RELEASE, "agent");
;             asm volatile("s_waitcnt vmcnt(0)" ::: "memory");
;             const unsigned og = xb_add(&bar[XB_TOP], 1u);
;             const unsigned tg = og / nx;
;             if (og + 1u == (tg + 1u) * nx) xb_add(&bar[XB_TOPGEN], 1u);
;             else XB_SPIN(xb_ld(&bar[XB_TOPGEN]) == tg, bar);
;             __builtin_amdgcn_fence(__ATOMIC_ACQUIRE, "agent");
;             xb_add(&bar[XB_XGEN(b.x)], 1u);
;             asm volatile("s_waitcnt vmcnt(0)" ::: "memory");
;         } else {
;             XB_SPIN(xb_ld(&bar[XB_XGEN(b.x)]) == gen, bar);
.LBB0_200:
	v_readlane_b32 s4, v254, 3
	s_lshl_b32 s4, s4, 8
	s_add_u32 s4, s92, s4
	s_addc_u32 s5, s93, 0
	v_mov_b32_e32 v1, 0x1000
	v_mov_b32_e32 v3, 1
	global_atomic_add v3, v1, v3, s[4:5] offset:1024 sc0
	v_cvt_f32_u32_e32 v1, v2
	v_sub_u32_e32 v4, 0, v2
	v_rcp_iflag_f32_e32 v1, v1
	s_nop 0
	v_mul_f32_e32 v1, 0x4f7ffffe, v1
	v_cvt_u32_f32_e32 v1, v1
	v_mul_lo_u32 v4, v4, v1
	v_mul_hi_u32 v4, v1, v4
	v_add_u32_e32 v1, v1, v4
	s_waitcnt vmcnt(0)
	v_mul_hi_u32 v1, v3, v1
	v_mul_lo_u32 v4, v1, v2
	v_sub_u32_e32 v4, v3, v4
	v_add_u32_e32 v5, 1, v1
	v_cmp_ge_u32_e32 vcc, v4, v2
	v_add_u32_e32 v3, 1, v3
	s_nop 0
	v_cndmask_b32_e32 v1, v1, v5, vcc
	v_sub_u32_e32 v5, v4, v2
	v_cndmask_b32_e32 v4, v4, v5, vcc
	v_add_u32_e32 v5, 1, v1
	v_cmp_ge_u32_e32 vcc, v4, v2
	s_nop 1
	v_cndmask_b32_e32 v1, v1, v5, vcc
	v_mul_lo_u32 v4, v2, v1
	v_add_u32_e32 v2, v4, v2
	v_cmp_ne_u32_e32 vcc, v3, v2
	s_and_saveexec_b64 s[6:7], vcc
	s_xor_b64 s[6:7], exec, s[6:7]
	s_cbranch_execz .LBB0_214
	s_cmp_eq_u32 s98, 1
	s_cbranch_scc1 .Lsk2_nl
	s_waitcnt lgkmcnt(0)
	v_mov_b32_e32 v0, 0x2000
	global_load_dword v0, v0, s[4:5] offset:1024 sc1
	s_add_u32 s12, s4, 0x2400
	s_addc_u32 s13, s5, 0
	s_waitcnt vmcnt(0)
	v_cmp_eq_u32_e32 vcc, v0, v1
	s_and_saveexec_b64 s[8:9], vcc
	s_cbranch_execz .LBB0_213
	s_add_u32 s10, s88, 0xffc0200
	s_addc_u32 s11, s89, 0
	s_mov_b32 s24, 1
	s_mov_b64 s[14:15], 0
	v_mov_b32_e32 v0, 0
	s_branch .LBB0_204

; __device__ __forceinline__ unsigned xb_ld(unsigned* p)              { return __hip_atomic_load(p, __ATOMIC_RELAXED, __HIP_MEMORY_SCOPE_AGENT); }
; __device__ __forceinline__ unsigned xb_add(unsigned* p, unsigned v) { return __hip_atomic_fetch_add(p, v, __ATOMIC_RELAXED, __HIP_MEMORY_SCOPE_AGENT); }
; #define XB_SPIN(cond, bar) do { unsigned _sp = 0; while (cond) { __builtin_amdgcn_s_sleep(1); \
;     if ((++_sp & 255u) == 0u) { if (xb_ld(&(bar)[XB_TMO])) break; if (_sp > XB_SPIN_CAP) { atomicAdd(&(bar)[XB_TMO], 1u); break; } } } } while (0)
; __device__ __forceinline__ void xcd_barrier(const XcdBarrier& b) {
;     ...
;         const unsigned old = xb_add(&bar[XB_XSUB(b.x)], 1u);
;         const unsigned gen = old / nloc;
;         if (old + 1u == (gen + 1u) * nloc) {
;             __builtin_amdgcn_fence(__ATOMIC_RELEASE, "agent");
;             asm volatile("s_waitcnt vmcnt(0)" ::: "memory");
;             const unsigned og = xb_add(&bar[XB_TOP], 1u);
;             const unsigned tg = og / nx;
;             if (og + 1u == (tg + 1u) * nx) xb_add(&bar[XB_TOPGEN], 1u);
;             else XB_SPIN(xb_ld(&bar[XB_TOPGEN]) == tg, bar);
;             __builtin_amdgcn_fence(__ATOMIC_ACQUIRE, "agent");
;             xb_add(&bar[XB_XGEN(b.x)], 1u);
.LBB0_217:
	s_or_b64 exec, exec, s[8:9]
	v_cvt_f32_u32_e32 v3, v0
	s_waitcnt vmcnt(0)
	v_readfirstlane_b32 s6, v2
	s_add_u32 s8, s88, 0xffc3500
	s_addc_u32 s9, s89, 0
	v_rcp_iflag_f32_e32 v3, v3
	v_add_u32_e32 v1, s6, v1
	v_add_u32_e32 v4, 1, v1
	s_mov_b64 s[10:11], -1
	v_mul_f32_e32 v2, 0x4f7ffffe, v3
	v_cvt_u32_f32_e32 v2, v2
	v_sub_u32_e32 v3, 0, v0
	v_mul_lo_u32 v3, v3, v2
	v_mul_hi_u32 v3, v2, v3
	v_add_u32_e32 v2, v2, v3
	v_mul_hi_u32 v2, v1, v2
	v_mul_lo_u32 v3, v2, v0
	v_sub_u32_e32 v1, v1, v3
	v_add_u32_e32 v5, 1, v2
	v_cmp_ge_u32_e32 vcc, v1, v0
	v_sub_u32_e32 v3, v1, v0
	s_nop 0
	v_cndmask_b32_e32 v2, v2, v5, vcc
	v_cndmask_b32_e32 v1, v1, v3, vcc
	v_add_u32_e32 v3, 1, v2
	v_cmp_ge_u32_e32 vcc, v1, v0
	s_nop 1
	v_cndmask_b32_e32 v2, v2, v3, vcc
	v_mul_lo_u32 v1, v0, v2
	v_add_u32_e32 v0, v1, v0
	v_cmp_ne_u32_e32 vcc, v4, v0
	v_mov_b64_e32 v[0:1], s[8:9]
	s_and_saveexec_b64 s[6:7], vcc
	s_cbranch_execz .LBB0_229
	s_cmp_eq_u32 s98, 1
	s_cbranch_scc0 .Lsk2_ld_no
	s_mov_b64 s[14:15], 0
	s_branch .Lsk2_ld

; __device__ __forceinline__ void p2_mlstm(const Params& p, LAS unsigned char* lds) {
;     ...
;         if (tid == 0) {
;             float mprev = 0.f;
; #pragma unroll 1
;             for (int c = 0; c < 16; ++c) { const float mm = fmaxf(mprev, PCT[c]); MPREV[c] = mprev; MM127[c] = mm; mprev = PBT[c] + mm; }
;         }
;         u32x4 kreg[8], vreg, qfn[8];
;         const unsigned qoff = ((unsigned)(16 * wid + r) * 2048u + (unsigned)(h * 256 + 8 * q)) * 2u;
;         const unsigned koff = ((unsigned)(tid >> 5) * 2048u + 1024u + (unsigned)(h * 256) + (unsigned)(tid & 31) * 8u) * 2u;
;         const unsigned voff = ((unsigned)(tid >> 2) * 5120u + 2048u + (unsigned)(h * 256 + sl * 32) + (unsigned)(tid & 3) * 8u) * 2u;
;         const unsigned ooff = ((unsigned)(16 * wid + r) * 5120u + 3072u + (unsigned)(h * 256 + sl * 32 + 4 * q)) * 2u;
;         const unsigned hoff = ((unsigned)(16 * wid + r) * 1024u + (unsigned)(h * 256 + sl * 32 + 4 * q)) * 2u;
;         {
.LBB0_248:
	s_or_b64 exec, exec, s[34:35]
	s_cmp_eq_u32 s98, 1
	s_cbranch_scc0 .Lw2_done
	s_mov_b32 s98, 0
	v_readfirstlane_b32 s6, v212
	s_nop 3
	s_cmp_lg_u32 s6, 0
	s_cbranch_scc1 .Lw2_bar
	v_readlane_b32 s78, v254, 3
	v_readlane_b32 s6, v254, 43
	v_readlane_b32 s7, v254, 44
	s_nop 3
	s_lshl_b32 s78, s78, 8
	v_mov_b32_e32 v250, 0xffc3500
	v_mov_b32_e32 v251, 0xffc2400
	v_add_u32_e32 v251, s78, v251
	s_mov_b32 s78, 0
.Lw2_spin:
	global_load_dword v252, v250, s[6:7] sc1
	global_load_dword v253, v251, s[6:7] sc1
	s_waitcnt vmcnt(0)
	v_min_u32_e32 v252, v252, v253
	s_nop 1
	v_readfirstlane_b32 s80, v252
	s_nop 3
	s_cmp_ge_u32 s80, 3
	s_cbranch_scc1 .Lw2_acq
	s_sleep 1
	s_add_i32 s78, s78, 1
	s_cmp_lt_u32 s78, 0x40000
	s_cbranch_scc1 .Lw2_spin

; __device__ __forceinline__ void p2_mlstm(const Params& p, LAS unsigned char* lds) {
;     ...
;         u32x4 kreg[8], vreg, qfn[8];
;         const unsigned qoff = ((unsigned)(16 * wid + r) * 2048u + (unsigned)(h * 256 + 8 * q)) * 2u;
;         const unsigned koff = ((unsigned)(tid >> 5) * 2048u + 1024u + (unsigned)(h * 256) + (unsigned)(tid & 31) * 8u) * 2u;
;         const unsigned voff = ((unsigned)(tid >> 2) * 5120u + 2048u + (unsigned)(h * 256 + sl * 32) + (unsigned)(tid & 3) * 8u) * 2u;
;         const unsigned ooff = ((unsigned)(16 * wid + r) * 5120u + 3072u + (unsigned)(h * 256 + sl * 32 + 4 * q)) * 2u;
;         const unsigned hoff = ((unsigned)(16 * wid + r) * 1024u + (unsigned)(h * 256 + sl * 32 + 4 * q)) * 2u;
;         {
;             const bf16_t* qkc = QK + (size_t)tokbase * 2048; const bf16_t* r1c = R1 + (size_t)tokbase * 5120;
; #pragma unroll
;             for (int kk = 0; kk < 8; ++kk) qfn[kk] = ldg16(qkc, qoff + 64u * kk);
; #pragma unroll
;             for (int i = 0; i < 8; ++i) kreg[i] = ldg16(qkc, koff + 65536u * i);
;             vreg = ldg16(r1c, voff);
;         }
;         __syncthreads();
.Lw2_done:
	s_bfe_u32 s78, s84, 0x30003
	s_lshl_b32 s1, s33, 9
	s_and_b32 s80, s1, 0x3800
	s_lshl_b32 s6, s82, 8
	s_lshl_b32 s7, s78, 5
	s_ashr_i32 s1, s0, 31
	v_writelane_b32 v254, s33, 61
	s_lshl_b32 s81, s78, 6
	v_or_b32_e32 v5, s6, v203
	s_or_b32 s33, s7, s6
	s_lshl_b64 s[34:35], s[0:1], 12
	v_lshlrev_b32_e32 v160, 1, v5
	v_or_b32_e32 v5, s6, v193
	s_add_u32 s34, s94, s34
	v_lshlrev_b32_e32 v162, 1, v5
	s_addc_u32 s35, s95, s35
	v_mov_b32_e32 v163, v4
	v_lshl_add_u64 v[6:7], s[34:35], 0, v[162:163]
	s_mov_b32 s40, 0x10000
	v_add_co_u32_e32 v44, vcc, s40, v6
	s_mov_b32 s79, 0x50000
	s_nop 0
	v_addc_co_u32_e32 v45, vcc, 0, v7, vcc
	v_add_co_u32_e32 v48, vcc, s37, v6
	global_load_dwordx4 v[8:11], v160, s[34:35] offset:64
	global_load_dwordx4 v[12:15], v160, s[34:35] offset:128
	global_load_dwordx4 v[16:19], v160, s[34:35] offset:192
	global_load_dwordx4 v[20:23], v160, s[34:35] offset:256
	global_load_dwordx4 v[24:27], v160, s[34:35] offset:320
	global_load_dwordx4 v[32:35], v160, s[34:35] offset:384
	global_load_dwordx4 v[36:39], v160, s[34:35] offset:448
	v_addc_co_u32_e32 v49, vcc, 0, v7, vcc
	v_add_co_u32_e32 v60, vcc, s79, v6
	s_mov_b32 s79, 0x70000
	s_nop 0
	v_addc_co_u32_e32 v61, vcc, 0, v7, vcc
	v_add_co_u32_e32 v6, vcc, s79, v6
	s_mul_hi_i32 s1, s0, 0x2800
	s_nop 0
	v_addc_co_u32_e32 v7, vcc, 0, v7, vcc
	s_mulk_i32 s0, 0x2800
	v_readlane_b32 vcc_lo, v254, 20
	v_or_b32_e32 v5, s33, v194
	v_or_b32_e32 v164, 0x20800, v162
	v_or_b32_e32 v168, 0x60800, v162
	v_readlane_b32 vcc_hi, v254, 21
	s_add_u32 s0, vcc_lo, s0
	global_load_dwordx4 v[28:31], v160, s[34:35]
	global_load_dwordx4 v[40:43], v162, s[34:35] offset:2048
	s_nop 0
	global_load_dwordx4 v[44:47], v[44:45], off offset:2048
	s_nop 0
	global_load_dwordx4 v[52:55], v[48:49], off offset:2048
	v_or_b32_e32 v166, 0x40800, v162
	global_load_dwordx4 v[48:51], v164, s[34:35]
	global_load_dwordx4 v[56:59], v166, s[34:35]
	s_nop 0
	global_load_dwordx4 v[60:63], v[60:61], off offset:2048
	s_nop 0
	global_load_dwordx4 v[64:67], v[6:7], off offset:2048
	v_lshlrev_b32_e32 v6, 1, v5
	s_addc_u32 s1, vcc_hi, s1
	global_load_dwordx4 v[68:71], v168, s[34:35]
	global_load_dwordx4 v[72:75], v6, s[0:1]
	s_lshl_b32 s0, s82, 5
	v_readlane_b32 s1, v254, 41
	s_add_u32 s0, s1, s0
	v_readlane_b32 s1, v254, 47
	s_addc_u32 s1, s1, 0
	s_lshl_b32 s34, s78, 2
	s_add_u32 s78, s0, s34
	s_addc_u32 s79, s1, 0
	s_lshl_b32 s0, s83, 9
	s_add_i32 s80, s80, s0
	v_or_b32_e32 v5, s33, v195
	v_mov_b32_e32 v7, v4
	s_and_b32 s0, s80, 0xfffff800
	v_lshl_add_u64 v[170:171], vcc, 0, v[6:7]
	v_lshlrev_b32_e32 v6, 2, v5
	s_ashr_i32 s1, s0, 31
	v_or_b32_e32 v5, s6, v195
	s_mov_b64 s[4:5], s[54:55]
	s_mov_b64 s[64:65], s[48:49]
	s_mov_b64 s[62:63], s[46:47]
	v_readlane_b32 s40, v254, 4
	s_or_b32 s80, s0, 0x80
	s_lshl_b64 s[34:35], s[0:1], 11
	v_or_b32_e32 v5, s7, v5
	v_readlane_b32 s6, v254, 23
	v_readlane_b32 s41, v254, 5
	v_readlane_b32 s42, v254, 6
	v_readlane_b32 s43, v254, 7
	v_readlane_b32 s7, v254, 24
	s_add_u32 s34, s6, s34
	v_readlane_b32 s52, v254, 16
	v_readlane_b32 s53, v254, 17
	s_addc_u32 s35, s7, s35
	s_mul_i32 s7, s0, 0x2800
	v_readlane_b32 s40, v254, 43
	v_lshl_add_u64 v[172:173], s[52:53], 0, v[6:7]
	global_load_dwordx4 v[100:103], v[172:173], off
	global_load_dwordx4 v[104:107], v[172:173], off offset:64
	v_lshlrev_b32_e32 v108, 2, v195
	v_add_u32_e32 v108, 0x24c00, v108
	s_waitcnt vmcnt(0)
	ds_write_b128 v108, v[100:103]
	ds_write_b128 v108, v[104:107] offset:64
	v_lshl_add_u32 v6, v5, 1, v217
	s_mul_hi_i32 s6, s0, 0x2800
	v_readlane_b32 s41, v254, 44
	s_add_u32 s0, s40, s7
	v_lshl_add_u64 v[174:175], s[34:35], 0, v[6:7]
	v_add_lshl_u32 v6, s33, v218, 1
	s_addc_u32 s1, s41, s6
	v_lshl_add_u64 v[176:177], s[0:1], 0, v[6:7]
	s_lshl_b32 s0, s82, 9
	s_or_b32 s33, s81, s0
	s_add_u32 s0, vcc_lo, s7
	v_readlane_b32 s46, v254, 10
	v_readlane_b32 s47, v254, 11
	v_readlane_b32 s48, v254, 12
	v_readlane_b32 s49, v254, 13
	v_readlane_b32 s54, v254, 18
	v_readlane_b32 s55, v254, 19
	v_add_u32_e32 v6, s33, v219
	s_addc_u32 s1, vcc_hi, s6
	v_lshl_add_u64 v[178:179], s[0:1], 0, v[6:7]
	v_add_u32_e32 v6, s33, v220
	v_mov_b32_e32 v76, 0
	s_mov_b64 s[46:47], s[62:63]
	s_mov_b64 s[48:49], s[64:65]
	s_mov_b64 s[54:55], s[4:5]
	v_readlane_b32 s4, v254, 55
	v_readlane_b32 s62, v254, 57
	v_readlane_b32 s64, v254, 59
	v_mov_b32_e32 v161, v4
	s_mov_b32 s85, 0
	v_mov_b32_e32 v165, v4
	v_mov_b32_e32 v167, v4
	v_mov_b32_e32 v169, v4
	s_mov_b32 s7, 0x10000
	v_lshl_add_u64 v[180:181], s[0:1], 0, v[6:7]
	s_mov_b64 s[82:83], 0
	v_mov_b32_e32 v244, v221
	v_mov_b32_e32 v245, v197
	v_mov_b32_e32 v246, v216
	v_mov_b32_e32 v77, v76
	v_mov_b32_e32 v78, v76
	v_mov_b32_e32 v79, v76
	v_mov_b32_e32 v96, v76
	v_mov_b32_e32 v97, v76
	v_mov_b32_e32 v98, v76
	v_mov_b32_e32 v99, v76
	v_mov_b32_e32 v92, v76
	v_mov_b32_e32 v93, v76
	v_mov_b32_e32 v94, v76
	v_mov_b32_e32 v95, v76
	v_mov_b32_e32 v88, v76
	v_mov_b32_e32 v89, v76
	v_mov_b32_e32 v90, v76
	v_mov_b32_e32 v91, v76
	v_mov_b32_e32 v84, v76
	v_mov_b32_e32 v85, v76
	v_mov_b32_e32 v86, v76
	v_mov_b32_e32 v87, v76
	v_mov_b32_e32 v80, v76
	v_mov_b32_e32 v81, v76
	v_mov_b32_e32 v82, v76
	v_mov_b32_e32 v83, v76
	v_readlane_b32 s5, v254, 56
	v_readlane_b32 s63, v254, 58
	v_readlane_b32 s65, v254, 60
	s_waitcnt lgkmcnt(0)
	s_barrier
	v_readlane_b32 s44, v254, 8
	v_readlane_b32 s45, v254, 9
	v_readlane_b32 s50, v254, 14
	v_readlane_b32 s51, v254, 15
	v_readlane_b32 s42, v254, 45
	v_readlane_b32 s43, v254, 46
	s_branch .LBB0_250
